# P1, out-proj, down GEMMs: per-unit next-offset lane arithmetic replaced by a per-phase base VGPR
# baseline (speedup 1.0000x reference)
.LBB0_55:
	s_mov_b64 s[14:15], 0x80
	s_bfe_u32 s6, s76, 0x20006
	s_add_i32 m0, s34, 0x18000
	v_lshl_add_u64 v[6:7], v[6:7], 0, s[14:15]
	s_lshl_b32 s7, s6, 12
	s_waitcnt vmcnt(2)
	s_barrier
	global_load_lds_dwordx4 v[6:7], off
	v_lshl_add_u64 v[4:5], v[4:5], 0, s[14:15]
	s_add_i32 m0, s34, 0x1a000
	s_add_i32 s42, s34, 0x8000
	s_add_i32 s43, s34, 0xa000
	global_load_lds_dwordx4 v[4:5], off
	v_lshl_add_u64 v[0:1], v[0:1], 0, s[14:15]
	s_mov_b32 m0, s42
	s_add_u32 s4, s0, 0x40080
	global_load_lds_dwordx4 v[0:1], off
	v_lshl_add_u64 v[0:1], v[2:3], 0, s[14:15]
	s_mov_b32 m0, s43
	s_addc_u32 s5, s1, 0
	global_load_lds_dwordx4 v[0:1], off
	s_add_i32 m0, s34, 0x1c000
	v_lshl_add_u64 v[0:1], s[4:5], 0, v[160:161]
	global_load_lds_dwordx4 v[0:1], off
	v_lshl_add_u64 v[0:1], s[4:5], 0, v[162:163]
	s_add_i32 m0, s34, 0x1e000
	v_and_b32_e32 v2, 48, v8
	global_load_lds_dwordx4 v[0:1], off
	v_and_b32_e32 v0, 15, v8
	v_or_b32_e32 v1, s91, v0
	v_lshlrev_b32_e32 v3, 6, v1
	s_movk_i32 s4, 0x3c0
	v_and_or_b32 v3, v3, s4, v2
	v_lshlrev_b32_e32 v1, 2, v1
	v_lshl_or_b32 v0, v0, 6, v2
	v_lshlrev_b32_e32 v2, 2, v8
	s_cmpk_lt_u32 s76, 0x100
	v_and_b32_e32 v1, 32, v1
	v_readlane_b32 s4, v253, 38
	v_and_b32_e32 v2, 32, v2
	s_cselect_b64 s[16:17], -1, 0
	s_bitcmp0_b32 s76, 6
	v_bitop3_b32 v1, v3, s4, v1 bitop3:0xde
	v_bitop3_b32 v176, v0, s7, v2 bitop3:0xde
	s_cselect_b64 s[18:19], -1, 0
	s_lshl_b32 s4, s6, 6
	v_add_u32_e32 v0, 64, v246
	s_add_u32 s45, s96, s4
	v_cmp_lt_i32_e32 vcc, v241, v0
	s_waitcnt vmcnt(6)
	s_addc_u32 s46, s97, 0
	s_add_u32 s47, s66, 0x19400080
	v_cndmask_b32_e32 v0, v174, v241, vcc
	v_lshlrev_b32_e32 v177, 2, v0
	v_add_u32_e32 v0, 0, v176
	s_mov_b32 s44, 0x8000
	s_addc_u32 s48, s67, 0
	v_add_u32_e32 v178, 0x10000, v0
	v_add_u32_e32 v179, 0x14000, v0
	v_add_u32_e32 v180, 0, v1
	s_add_i32 s49, s34, 0xc000
	s_add_i32 s50, s34, 0xe000
	v_mov_b32_e32 v181, 0x1fcf
	v_mov_b32_e32 v182, 0xfcf
	v_mov_b32_e32 v183, 0x1fdf
	v_mov_b32_e32 v184, 0xfdf
	v_mov_b32_e32 v185, 0x1fef
	v_mov_b32_e32 v186, 0xfef
	v_mov_b32_e32 v187, 0x1fff
	v_mov_b32_e32 v188, 0xfff
	s_mov_b32 s51, 0
	s_barrier
	v_add_u32_e32 v247, s33, v174
	v_bfe_u32 v248, v247, 6, 1
	v_and_b32_e32 v249, 3, v247
	v_bfe_u32 v250, v247, 5, 1
	v_lshlrev_b32_e32 v249, 4, v249
	v_lshlrev_b32_e32 v250, 5, v250
	v_xor_b32_e32 v249, v249, v250
	v_lshl_add_u32 v248, v248, 6, v249
	v_lshrrev_b32_e32 v249, 7, v247
	v_bfe_u32 v247, v247, 2, 4
	v_lshl_add_u32 v247, v249, 4, v247
	v_lshl_add_u32 v247, v247, 11, v248
	s_branch .LBB0_58

.LBB0_61:
	ds_read_b128 v[144:147], v178
	ds_read_b128 v[148:151], v178 offset:1024
	ds_read_b128 v[152:155], v178 offset:2048
	ds_read_b128 v[156:159], v178 offset:3072
	ds_read_b128 v[128:131], v179
	ds_read_b128 v[132:135], v179 offset:1024
	ds_read_b128 v[136:139], v179 offset:2048
	ds_read_b128 v[140:143], v179 offset:3072
	s_cmp_eq_u32 s54, 12
	s_cselect_b64 s[6:7], -1, 0
	s_add_u32 s4, s47, s0
	s_addc_u32 s5, s48, s1
	s_mov_b32 m0, s49
	ds_read_b128 v[190:193], v180
	ds_read_b128 v[194:197], v180 offset:1024
	ds_read_b128 v[198:201], v180 offset:2048
	ds_read_b128 v[202:205], v180 offset:3072
	ds_read_b128 v[206:209], v180 offset:4096
	ds_read_b128 v[210:213], v180 offset:5120
	ds_read_b128 v[214:217], v180 offset:6144
	ds_read_b128 v[218:221], v180 offset:7168
	global_load_lds_dwordx4 v168, s[4:5]
	s_mov_b32 m0, s50
	s_nop 0
	global_load_lds_dwordx4 v170, s[4:5]
	s_waitcnt vmcnt(8)
	s_waitcnt lgkmcnt(0)
	s_barrier
	s_setprio 1
	s_waitcnt lgkmcnt(0)
	v_mfma_f32_16x16x32_bf16 v[124:127], v[144:147], v[190:193], v[124:127]
	v_mfma_f32_16x16x32_bf16 v[120:123], v[152:155], v[190:193], v[120:123]
	v_mfma_f32_16x16x32_bf16 v[108:111], v[144:147], v[198:201], v[108:111]
	v_mfma_f32_16x16x32_bf16 v[104:107], v[152:155], v[198:201], v[104:107]
	v_mfma_f32_16x16x32_bf16 v[92:95], v[144:147], v[206:209], v[92:95]
	v_mfma_f32_16x16x32_bf16 v[88:91], v[152:155], v[206:209], v[88:91]
	v_mfma_f32_16x16x32_bf16 v[76:79], v[144:147], v[214:217], v[76:79]
	v_mfma_f32_16x16x32_bf16 v[72:75], v[152:155], v[214:217], v[72:75]
	v_mfma_f32_16x16x32_bf16 v[124:127], v[148:151], v[194:197], v[124:127]
	v_mfma_f32_16x16x32_bf16 v[120:123], v[156:159], v[194:197], v[120:123]
	v_mfma_f32_16x16x32_bf16 v[108:111], v[148:151], v[202:205], v[108:111]
	v_mfma_f32_16x16x32_bf16 v[104:107], v[156:159], v[202:205], v[104:107]
	v_mfma_f32_16x16x32_bf16 v[92:95], v[148:151], v[210:213], v[92:95]
	v_mfma_f32_16x16x32_bf16 v[88:91], v[156:159], v[210:213], v[88:91]
	v_mfma_f32_16x16x32_bf16 v[76:79], v[148:151], v[218:221], v[76:79]
	v_mfma_f32_16x16x32_bf16 v[72:75], v[156:159], v[218:221], v[72:75]
	v_mfma_f32_16x16x32_bf16 v[116:119], v[128:131], v[190:193], v[116:119]
	v_mfma_f32_16x16x32_bf16 v[112:115], v[136:139], v[190:193], v[112:115]
	v_mfma_f32_16x16x32_bf16 v[100:103], v[128:131], v[198:201], v[100:103]
	v_mfma_f32_16x16x32_bf16 v[96:99], v[136:139], v[198:201], v[96:99]
	v_mfma_f32_16x16x32_bf16 v[84:87], v[128:131], v[206:209], v[84:87]
	v_mfma_f32_16x16x32_bf16 v[80:83], v[136:139], v[206:209], v[80:83]
	v_mfma_f32_16x16x32_bf16 v[68:71], v[128:131], v[214:217], v[68:71]
	v_mfma_f32_16x16x32_bf16 v[64:67], v[136:139], v[214:217], v[64:67]
	v_mfma_f32_16x16x32_bf16 v[116:119], v[132:135], v[194:197], v[116:119]
	v_mfma_f32_16x16x32_bf16 v[112:115], v[140:143], v[194:197], v[112:115]
	v_mfma_f32_16x16x32_bf16 v[100:103], v[132:135], v[202:205], v[100:103]
	v_mfma_f32_16x16x32_bf16 v[96:99], v[140:143], v[202:205], v[96:99]
	v_mfma_f32_16x16x32_bf16 v[84:87], v[132:135], v[210:213], v[84:87]
	v_mfma_f32_16x16x32_bf16 v[80:83], v[140:143], v[210:213], v[80:83]
	v_mfma_f32_16x16x32_bf16 v[68:71], v[132:135], v[218:221], v[68:71]
	v_mfma_f32_16x16x32_bf16 v[64:67], v[140:143], v[218:221], v[64:67]
	s_setprio 0
	s_barrier
	s_and_b64 s[4:5], s[22:23], s[6:7]
	s_andn2_b64 vcc, exec, s[4:5]
	s_cbranch_vccnz .LBB0_63
	s_lshl_b32 s57, s29, 11
	s_lshl_b32 s58, s30, 11
	v_add_u32_e32 v164, s57, v247
	v_add_u32_e32 v168, s58, v247
	v_add_u32_e32 v166, 0x20000, v164
	v_add_u32_e32 v170, 0x20000, v168
	v_mov_b32_e32 v171, v165
	v_mov_b32_e32 v172, v168
	v_mov_b32_e32 v173, v165
	s_branch .LBB0_64

.LBB0_715:
	s_mov_b64 s[6:7], 0x80
	s_add_i32 m0, s27, 0x18000
	v_lshl_add_u64 v[6:7], v[6:7], 0, s[6:7]
	s_waitcnt vmcnt(2)
	s_barrier
	global_load_lds_dwordx4 v[6:7], off
	v_lshl_add_u64 v[4:5], v[4:5], 0, s[6:7]
	s_add_i32 m0, s27, 0x1a000
	s_add_i32 s37, s27, 0x8000
	s_add_i32 s38, s27, 0xa000
	global_load_lds_dwordx4 v[4:5], off
	v_lshl_add_u64 v[0:1], v[0:1], 0, s[6:7]
	s_mov_b32 m0, s37
	s_add_u32 s8, s20, 0x40080
	global_load_lds_dwordx4 v[0:1], off
	v_lshl_add_u64 v[0:1], v[2:3], 0, s[6:7]
	s_mov_b32 m0, s38
	s_addc_u32 s9, s21, 0
	global_load_lds_dwordx4 v[0:1], off
	s_add_i32 m0, s27, 0x1c000
	v_lshl_add_u64 v[0:1], s[8:9], 0, v[162:163]
	global_load_lds_dwordx4 v[0:1], off
	v_lshl_add_u64 v[0:1], s[8:9], 0, v[160:161]
	s_add_i32 m0, s27, 0x1e000
	s_sext_i32_i8 s45, s0
	global_load_lds_dwordx4 v[0:1], off
	v_and_b32_e32 v0, 15, v8
	v_or_b32_e32 v1, s91, v0
	v_and_b32_e32 v2, 48, v8
	v_lshlrev_b32_e32 v3, 6, v1
	s_movk_i32 s0, 0x3c0
	v_and_or_b32 v3, v3, s0, v2
	v_lshl_or_b32 v0, v0, 6, v2
	v_lshlrev_b32_e32 v2, 2, v8
	s_cmpk_lt_u32 s76, 0x100
	v_lshlrev_b32_e32 v1, 2, v1
	v_and_b32_e32 v2, 32, v2
	s_cselect_b64 s[8:9], -1, 0
	s_add_u32 s10, s66, 0xf800000
	v_and_b32_e32 v1, 32, v1
	v_readlane_b32 s0, v253, 38
	v_bitop3_b32 v176, v0, s74, v2 bitop3:0xde
	s_waitcnt vmcnt(6)
	s_addc_u32 s11, s67, 0
	v_bitop3_b32 v1, v3, s0, v1 bitop3:0xde
	s_add_u32 s40, s66, 0x19400080
	v_add_u32_e32 v0, 0, v176
	s_mov_b32 s39, 0x8000
	s_addc_u32 s41, s67, 0
	v_add_u32_e32 v177, 0x10000, v0
	v_add_u32_e32 v178, 0x14000, v0
	v_add_u32_e32 v179, 0, v1
	s_mov_b32 s12, 0x3f9837f0
	s_mov_b32 s42, 0
	s_barrier
	v_add_u32_e32 v247, s33, v174
	v_bfe_u32 v248, v247, 6, 1
	v_and_b32_e32 v249, 3, v247
	v_bfe_u32 v250, v247, 5, 1
	v_lshlrev_b32_e32 v249, 4, v249
	v_lshlrev_b32_e32 v250, 5, v250
	v_xor_b32_e32 v249, v249, v250
	v_lshl_add_u32 v248, v248, 6, v249
	v_lshrrev_b32_e32 v249, 7, v247
	v_bfe_u32 v247, v247, 2, 4
	v_lshl_add_u32 v247, v249, 4, v247
	v_lshl_add_u32 v247, v247, 11, v248
	s_branch .LBB0_718

.LBB0_721:
	ds_read_b128 v[144:147], v177
	ds_read_b128 v[148:151], v177 offset:1024
	ds_read_b128 v[152:155], v177 offset:2048
	ds_read_b128 v[156:159], v177 offset:3072
	ds_read_b128 v[128:131], v178
	ds_read_b128 v[132:135], v178 offset:1024
	ds_read_b128 v[136:139], v178 offset:2048
	ds_read_b128 v[140:143], v178 offset:3072
	s_cmp_eq_u32 s51, 12
	s_cselect_b64 s[24:25], -1, 0
	s_add_i32 m0, s27, 0xc000
	s_add_u32 s22, s40, s20
	s_addc_u32 s23, s41, s21
	ds_read_b128 v[180:183], v179
	ds_read_b128 v[184:187], v179 offset:1024
	ds_read_b128 v[188:191], v179 offset:2048
	ds_read_b128 v[192:195], v179 offset:3072
	ds_read_b128 v[196:199], v179 offset:4096
	ds_read_b128 v[200:203], v179 offset:5120
	ds_read_b128 v[204:207], v179 offset:6144
	ds_read_b128 v[208:211], v179 offset:7168
	global_load_lds_dwordx4 v168, s[22:23]
	s_add_i32 m0, s27, 0xe000
	s_nop 0
	global_load_lds_dwordx4 v170, s[22:23]
	s_waitcnt vmcnt(8)
	s_waitcnt lgkmcnt(0)
	s_barrier
	s_setprio 1
	s_waitcnt lgkmcnt(0)
	v_mfma_f32_16x16x32_bf16 v[124:127], v[144:147], v[180:183], v[124:127]
	v_mfma_f32_16x16x32_bf16 v[120:123], v[152:155], v[180:183], v[120:123]
	v_mfma_f32_16x16x32_bf16 v[112:115], v[144:147], v[188:191], v[112:115]
	v_mfma_f32_16x16x32_bf16 v[104:107], v[152:155], v[188:191], v[104:107]
	v_mfma_f32_16x16x32_bf16 v[96:99], v[144:147], v[196:199], v[96:99]
	v_mfma_f32_16x16x32_bf16 v[88:91], v[152:155], v[196:199], v[88:91]
	v_mfma_f32_16x16x32_bf16 v[80:83], v[144:147], v[204:207], v[80:83]
	v_mfma_f32_16x16x32_bf16 v[72:75], v[152:155], v[204:207], v[72:75]
	v_mfma_f32_16x16x32_bf16 v[124:127], v[148:151], v[184:187], v[124:127]
	v_mfma_f32_16x16x32_bf16 v[120:123], v[156:159], v[184:187], v[120:123]
	v_mfma_f32_16x16x32_bf16 v[112:115], v[148:151], v[192:195], v[112:115]
	v_mfma_f32_16x16x32_bf16 v[104:107], v[156:159], v[192:195], v[104:107]
	v_mfma_f32_16x16x32_bf16 v[96:99], v[148:151], v[200:203], v[96:99]
	v_mfma_f32_16x16x32_bf16 v[88:91], v[156:159], v[200:203], v[88:91]
	v_mfma_f32_16x16x32_bf16 v[80:83], v[148:151], v[208:211], v[80:83]
	v_mfma_f32_16x16x32_bf16 v[72:75], v[156:159], v[208:211], v[72:75]
	v_mfma_f32_16x16x32_bf16 v[116:119], v[128:131], v[180:183], v[116:119]
	v_mfma_f32_16x16x32_bf16 v[108:111], v[136:139], v[180:183], v[108:111]
	v_mfma_f32_16x16x32_bf16 v[100:103], v[128:131], v[188:191], v[100:103]
	v_mfma_f32_16x16x32_bf16 v[92:95], v[136:139], v[188:191], v[92:95]
	v_mfma_f32_16x16x32_bf16 v[84:87], v[128:131], v[196:199], v[84:87]
	v_mfma_f32_16x16x32_bf16 v[76:79], v[136:139], v[196:199], v[76:79]
	v_mfma_f32_16x16x32_bf16 v[68:71], v[128:131], v[204:207], v[68:71]
	v_mfma_f32_16x16x32_bf16 v[64:67], v[136:139], v[204:207], v[64:67]
	v_mfma_f32_16x16x32_bf16 v[116:119], v[132:135], v[184:187], v[116:119]
	v_mfma_f32_16x16x32_bf16 v[108:111], v[140:143], v[184:187], v[108:111]
	v_mfma_f32_16x16x32_bf16 v[100:103], v[132:135], v[192:195], v[100:103]
	v_mfma_f32_16x16x32_bf16 v[92:95], v[140:143], v[192:195], v[92:95]
	v_mfma_f32_16x16x32_bf16 v[84:87], v[132:135], v[200:203], v[84:87]
	v_mfma_f32_16x16x32_bf16 v[76:79], v[140:143], v[200:203], v[76:79]
	v_mfma_f32_16x16x32_bf16 v[68:71], v[132:135], v[208:211], v[68:71]
	v_mfma_f32_16x16x32_bf16 v[64:67], v[140:143], v[208:211], v[64:67]
	s_setprio 0
	s_barrier
	s_and_b64 s[22:23], s[16:17], s[24:25]
	s_andn2_b64 vcc, exec, s[22:23]
	s_cbranch_vccnz .LBB0_723
	s_lshl_b32 s57, s47, 11
	s_lshl_b32 s58, s48, 11
	v_add_u32_e32 v164, s57, v247
	v_add_u32_e32 v168, s58, v247
	v_add_u32_e32 v166, 0x20000, v164
	v_add_u32_e32 v170, 0x20000, v168
	v_mov_b32_e32 v171, v165
	v_mov_b32_e32 v172, v168
	v_mov_b32_e32 v173, v165
	s_branch .LBB0_724

.LBB0_1316:
	s_add_u32 s8, s66, 0xf80000
	s_mov_b64 s[10:11], 0x80
	s_addc_u32 s9, s67, 0
	s_add_i32 m0, s25, 0x18000
	v_lshl_add_u64 v[4:5], v[4:5], 0, s[10:11]
	s_waitcnt vmcnt(2)
	s_barrier
	global_load_lds_dwordx4 v[4:5], off
	v_lshl_add_u64 v[2:3], v[2:3], 0, s[10:11]
	s_add_i32 m0, s25, 0x1a000
	s_add_i32 s36, s25, 0x8000
	s_add_i32 s37, s25, 0xa000
	global_load_lds_dwordx4 v[2:3], off
	v_lshl_add_u64 v[0:1], v[0:1], 0, s[10:11]
	s_mov_b32 m0, s36
	s_add_u32 s0, s18, 0x58080
	global_load_lds_dwordx4 v[0:1], off
	v_lshl_add_u64 v[0:1], v[6:7], 0, s[10:11]
	s_mov_b32 m0, s37
	s_addc_u32 s1, s19, 0
	global_load_lds_dwordx4 v[0:1], off
	s_add_i32 m0, s25, 0x1c000
	v_lshl_add_u64 v[0:1], s[0:1], 0, v[162:163]
	global_load_lds_dwordx4 v[0:1], off
	v_lshl_add_u64 v[0:1], s[0:1], 0, v[160:161]
	s_add_i32 m0, s25, 0x1e000
	v_and_b32_e32 v2, 48, v8
	global_load_lds_dwordx4 v[0:1], off
	v_and_b32_e32 v0, 15, v8
	v_or_b32_e32 v1, s91, v0
	v_lshlrev_b32_e32 v3, 6, v1
	s_movk_i32 s0, 0x3c0
	v_and_or_b32 v3, v3, s0, v2
	v_lshl_or_b32 v0, v0, 6, v2
	v_lshlrev_b32_e32 v2, 2, v8
	v_lshlrev_b32_e32 v1, 2, v1
	v_and_b32_e32 v2, 32, v2
	v_and_b32_e32 v1, 32, v1
	v_readlane_b32 s0, v253, 38
	v_bitop3_b32 v173, v0, s74, v2 bitop3:0xde
	s_waitcnt vmcnt(6)
	s_cmpk_lt_u32 s76, 0x100
	v_bitop3_b32 v1, v3, s0, v1 bitop3:0xde
	s_cselect_b64 s[12:13], -1, 0
	s_add_u32 s38, s66, 0x19400080
	v_add_u32_e32 v0, 0, v173
	s_mov_b32 s69, s5
	s_addc_u32 s39, s67, 0
	v_add_u32_e32 v175, 0x10000, v0
	v_add_u32_e32 v176, 0x14000, v0
	v_add_u32_e32 v177, 0, v1
	s_add_i32 s40, s25, 0xc000
	s_add_i32 s41, s25, 0xe000
	s_mov_b32 s42, 0
	s_barrier
	v_add_u32_e32 v247, s33, v174
	v_bfe_u32 v248, v247, 6, 1
	v_and_b32_e32 v249, 3, v247
	v_bfe_u32 v250, v247, 5, 1
	v_lshlrev_b32_e32 v249, 4, v249
	v_lshlrev_b32_e32 v250, 5, v250
	v_xor_b32_e32 v249, v249, v250
	v_lshl_add_u32 v248, v248, 6, v249
	v_lshrrev_b32_e32 v249, 7, v247
	v_bfe_u32 v247, v247, 2, 4
	v_lshl_add_u32 v247, v249, 4, v247
	v_mul_u32_u24_e32 v247, 0xb00, v247
	v_add_u32_e32 v247, v247, v248
	s_branch .LBB0_1319

.LBB0_1324:
	ds_read_b128 v[16:19], v175
	ds_read_b128 v[20:23], v175 offset:1024
	ds_read_b128 v[24:27], v175 offset:2048
	ds_read_b128 v[28:31], v175 offset:3072
	ds_read_b128 v[0:3], v176
	ds_read_b128 v[4:7], v176 offset:1024
	ds_read_b128 v[8:11], v176 offset:2048
	ds_read_b128 v[12:15], v176 offset:3072
	s_cmp_eq_u32 s52, 18
	s_cselect_b64 s[22:23], -1, 0
	s_add_u32 s20, s38, s18
	s_addc_u32 s21, s39, s19
	s_mov_b32 m0, s40
	ds_read_b128 v[178:181], v177
	ds_read_b128 v[182:185], v177 offset:1024
	ds_read_b128 v[186:189], v177 offset:2048
	ds_read_b128 v[190:193], v177 offset:3072
	ds_read_b128 v[194:197], v177 offset:4096
	ds_read_b128 v[198:201], v177 offset:5120
	ds_read_b128 v[202:205], v177 offset:6144
	ds_read_b128 v[206:209], v177 offset:7168
	global_load_lds_dwordx4 v166, s[20:21]
	s_mov_b32 m0, s41
	s_nop 0
	global_load_lds_dwordx4 v170, s[20:21]
	s_waitcnt vmcnt(8)
	s_waitcnt lgkmcnt(0)
	s_barrier
	s_setprio 1
	s_waitcnt lgkmcnt(0)
	v_mfma_f32_16x16x128_f8f6f4 v[156:159], v[16:23], v[178:185], v[156:159]
	v_mfma_f32_16x16x128_f8f6f4 v[152:155], v[24:31], v[178:185], v[152:155]
	v_mfma_f32_16x16x128_f8f6f4 v[140:143], v[16:23], v[186:193], v[140:143]
	v_mfma_f32_16x16x128_f8f6f4 v[136:139], v[24:31], v[186:193], v[136:139]
	v_mfma_f32_16x16x128_f8f6f4 v[124:127], v[16:23], v[194:201], v[124:127]
	v_mfma_f32_16x16x128_f8f6f4 v[120:123], v[24:31], v[194:201], v[120:123]
	v_mfma_f32_16x16x128_f8f6f4 v[108:111], v[16:23], v[202:209], v[108:111]
	v_mfma_f32_16x16x128_f8f6f4 v[104:107], v[24:31], v[202:209], v[104:107]
	v_mfma_f32_16x16x128_f8f6f4 v[148:151], v[0:7], v[178:185], v[148:151]
	v_mfma_f32_16x16x128_f8f6f4 v[144:147], v[8:15], v[178:185], v[144:147]
	v_mfma_f32_16x16x128_f8f6f4 v[132:135], v[0:7], v[186:193], v[132:135]
	v_mfma_f32_16x16x128_f8f6f4 v[128:131], v[8:15], v[186:193], v[128:131]
	v_mfma_f32_16x16x128_f8f6f4 v[116:119], v[0:7], v[194:201], v[116:119]
	v_mfma_f32_16x16x128_f8f6f4 v[112:115], v[8:15], v[194:201], v[112:115]
	v_mfma_f32_16x16x128_f8f6f4 v[100:103], v[0:7], v[202:209], v[100:103]
	v_mfma_f32_16x16x128_f8f6f4 v[96:99], v[8:15], v[202:209], v[96:99]
	s_setprio 0
	s_barrier
	s_and_b64 s[20:21], s[16:17], s[22:23]
	s_andn2_b64 vcc, exec, s[20:21]
	s_cbranch_vccnz .LBB0_1326
	s_mul_i32 s57, s48, s28
	s_mul_i32 s58, s49, s28
	v_add_u32_e32 v164, s57, v247
	v_add_u32_e32 v166, s58, v247
	v_add_u32_e32 v168, 0x2c000, v164
	v_add_u32_e32 v170, 0x2c000, v166
	v_mov_b32_e32 v167, v165
	v_mov_b32_e32 v171, v165
	v_mov_b32_e32 v169, v165
	s_branch .LBB0_1327
